# parallel grid-barrier polls with s_sleep 32 backoff between polls (GSYNC 2-6)
# speedup vs baseline: 1.0077x; 1.0077x over previous
.LBB0_385:
	v_mov_b64_e32 v[12:13], s[38:39]
	s_waitcnt lgkmcnt(0)
	global_load_dword v11, v[12:13], off offset:1024 sc1
	global_load_dword v0, v[12:13], off offset:1280 sc1
	global_load_dword v1, v[12:13], off offset:1536 sc1
	global_load_dword v2, v[12:13], off offset:1792 sc1
	global_load_dword v3, v[12:13], off offset:2048 sc1
	global_load_dword v4, v[12:13], off offset:2304 sc1
	global_load_dword v5, v[12:13], off offset:2560 sc1
	global_load_dword v6, v[12:13], off offset:2816 sc1
	global_load_dword v7, v[12:13], off offset:3072 sc1
	global_load_dword v8, v[12:13], off offset:3328 sc1
	global_load_dword v9, v[12:13], off offset:3584 sc1
	global_load_dword v10, v[12:13], off offset:3840 sc1
	v_mov_b64_e32 v[12:13], s[0:1]
	global_load_dword v12, v[12:13], off sc1
	v_mov_b64_e32 v[14:15], s[4:5]
	global_load_dword v13, v[14:15], off sc1
	v_mov_b64_e32 v[14:15], s[6:7]
	global_load_dword v14, v[14:15], off sc1
	v_mov_b64_e32 v[16:17], s[8:9]
	global_load_dword v15, v[16:17], off sc1
	s_or_b64 s[18:19], s[18:19], exec
	s_or_b64 s[16:17], s[16:17], exec
	s_waitcnt vmcnt(0) lgkmcnt(0)
	v_add_u32_e32 v16, v0, v11
	v_add_u32_e32 v16, v16, v1
	v_add_u32_e32 v16, v16, v2
	v_add_u32_e32 v16, v16, v3
	v_add_u32_e32 v16, v16, v4
	v_add_u32_e32 v16, v16, v5
	v_add_u32_e32 v16, v16, v6
	v_add_u32_e32 v16, v16, v7
	v_add_u32_e32 v16, v16, v8
	v_add_u32_e32 v16, v16, v9
	v_add_u32_e32 v16, v16, v10
	v_add_u32_e32 v16, v16, v12
	v_add_u32_e32 v16, v16, v13
	v_add_u32_e32 v16, v16, v14
	v_add_u32_e32 v16, v16, v15
	v_cmp_ne_u32_e32 vcc, s90, v16
	s_and_saveexec_b64 s[20:21], vcc
	s_cbranch_execz .LBB0_384
	s_and_b32 s24, s30, 0xff
	s_mov_b64 s[22:23], -1
	s_cmp_eq_u32 s24, 0
	s_mov_b64 s[26:27], -1
	s_mov_b64 s[24:25], -1
	s_sleep 32
	s_cbranch_scc1 .LBB0_388
	s_and_saveexec_b64 s[28:29], s[26:27]
	s_cbranch_execz .LBB0_383
	s_branch .LBB0_391

.LBB0_754:
	v_mov_b64_e32 v[12:13], s[40:41]
	s_waitcnt lgkmcnt(0)
	global_load_dword v11, v[12:13], off offset:1024 sc1
	global_load_dword v0, v[12:13], off offset:1280 sc1
	global_load_dword v1, v[12:13], off offset:1536 sc1
	global_load_dword v2, v[12:13], off offset:1792 sc1
	global_load_dword v3, v[12:13], off offset:2048 sc1
	global_load_dword v4, v[12:13], off offset:2304 sc1
	global_load_dword v5, v[12:13], off offset:2560 sc1
	global_load_dword v6, v[12:13], off offset:2816 sc1
	global_load_dword v7, v[12:13], off offset:3072 sc1
	global_load_dword v8, v[12:13], off offset:3328 sc1
	global_load_dword v9, v[12:13], off offset:3584 sc1
	global_load_dword v10, v[12:13], off offset:3840 sc1
	v_mov_b64_e32 v[12:13], s[0:1]
	global_load_dword v12, v[12:13], off sc1
	v_mov_b64_e32 v[14:15], s[4:5]
	global_load_dword v13, v[14:15], off sc1
	v_mov_b64_e32 v[14:15], s[8:9]
	global_load_dword v14, v[14:15], off sc1
	v_mov_b64_e32 v[16:17], s[10:11]
	global_load_dword v15, v[16:17], off sc1
	s_or_b64 s[20:21], s[20:21], exec
	s_or_b64 s[18:19], s[18:19], exec
	s_waitcnt vmcnt(0) lgkmcnt(0)
	v_add_u32_e32 v16, v0, v11
	v_add_u32_e32 v16, v16, v1
	v_add_u32_e32 v16, v16, v2
	v_add_u32_e32 v16, v16, v3
	v_add_u32_e32 v16, v16, v4
	v_add_u32_e32 v16, v16, v5
	v_add_u32_e32 v16, v16, v6
	v_add_u32_e32 v16, v16, v7
	v_add_u32_e32 v16, v16, v8
	v_add_u32_e32 v16, v16, v9
	v_add_u32_e32 v16, v16, v10
	v_add_u32_e32 v16, v16, v12
	v_add_u32_e32 v16, v16, v13
	v_add_u32_e32 v16, v16, v14
	v_add_u32_e32 v16, v16, v15
	v_cmp_ne_u32_e32 vcc, s90, v16
	s_and_saveexec_b64 s[22:23], vcc
	s_cbranch_execz .LBB0_753
	s_and_b32 s26, s33, 0xff
	s_mov_b64 s[24:25], -1
	s_cmp_eq_u32 s26, 0
	s_mov_b64 s[28:29], -1
	s_mov_b64 s[26:27], -1
	s_sleep 32
	s_cbranch_scc1 .LBB0_757
	s_and_saveexec_b64 s[30:31], s[28:29]
	s_cbranch_execz .LBB0_752
	s_branch .LBB0_760
